# scan: first three k-blocks of S-update operands requested inside the O-part tail
# baseline (speedup 1.0000x reference)
; #define LAS __attribute__((address_space(3)))
; __device__ __forceinline__ unsigned pk2(float lo, float hi) { const f32x2_t v = {lo, hi}; const bf16x2_t b = __builtin_convertvector(v, bf16x2_t); return __builtin_bit_cast(unsigned, b); }
; __device__ __forceinline__ bf16x8 cat8(const s16x4 a, const s16x4 b) { return __builtin_shufflevector(a, b, 0, 1, 2, 3, 4, 5, 6, 7); }
; __device__ __forceinline__ void hgrn_scan(const Params& p, LAS unsigned char* lds, int chain) {
;     ...
;         if (lat) {
;             bf16x8 sb[4];
; #pragma unroll
;             for (int ks = 0; ks < 4; ++ks) sb[ks] = pack_p(S[2 * ks], S[2 * ks + 1]);
;             bf16* orow = O + (long)hg_row(dir, b, 64 * c) * WA;
; #pragma unroll
;             for (int I = 0; I < 4; ++I) {
;                 f32x4 o = (f32x4){0.f, 0.f, 0.f, 0.f};
; #pragma unroll
;                 for (int ks = 0; ks < 4; ++ks) {
;                     const LAS unsigned char* ap = bb + SB_QD + (32 * ks + 4 * g + qq) * HP + (16 * I + 4 * pp) * 2;
;                     o = __builtin_amdgcn_mfma_f32_16x16x32_bf16(sb[ks], cat8(lds_tr(ap), lds_tr(ap + 16 * HP)), o, 0, 0, 0);
;                 }
; #pragma unroll
;                 for (int sp = 0; sp < 2; ++sp) {
;                     if (2 * sp > I) break;
;                     const LAS unsigned char* pr = bb + SB_P + (16 * I + li) * PP + (32 * sp + 4 * g) * 2;
;                     const u32x2 lo = *(const LAS u32x2*)pr; u32x2 hi = (u32x2){0u, 0u};
;                     if (2 * sp + 1 <= I) hi = *(const LAS u32x2*)(pr + 32);
;                     o = __builtin_amdgcn_mfma_f32_16x16x32_bf16(vf[sp], cat8u(lo, hi), o, 0, 0, 0);
;                 }
;                 { u32x2 w; w.x = pk2(o.x, o.y); w.y = pk2(o.z, o.w); *(u32x2*)(orow + (long)(16 * I + li) * ost) = w; }
;             }
;     ...
;         for (int blk = 0; blk < 8; ++blk) {
;             const f32x4 d4 = *(const LAS f32x4*)(bb + SB_D + (16 * blk + 4 * g) * 4);
;             f32x4 s = S[blk] * d4;
; #pragma unroll
;             for (int sp = 0; sp < 2; ++sp) {
;                 const LAS unsigned char* kp = bb + SB_KD + (16 * blk + li) * HPK + (32 * sp + 4 * g) * 2;
;                 s = __builtin_amdgcn_mfma_f32_16x16x32_bf16(cat8u(*(const LAS u32x2*)kp, *(const LAS u32x2*)(kp + 32)), vf[sp], s, 0, 0, 0);
.LBB0_410:
	s_andn2_b64 vcc, exec, s[18:19]
	s_cbranch_vccnz .LBB0_412
	v_cvt_pk_bf16_f32 v104, v76, v77
	v_cvt_pk_bf16_f32 v105, v78, v79
	v_cvt_pk_bf16_f32 v106, v92, v93
	v_cvt_pk_bf16_f32 v107, v94, v95
	v_add_u32_e32 v165, v139, v141
	v_cvt_pk_bf16_f32 v108, v80, v81
	v_cvt_pk_bf16_f32 v109, v82, v83
	v_cvt_pk_bf16_f32 v110, v88, v89
	v_cvt_pk_bf16_f32 v111, v90, v91
	ds_read_b64_tr_b16 v[176:177], v165 offset:2560
	ds_read_b64_tr_b16 v[174:175], v165
	ds_read_b64_tr_b16 v[178:179], v165 offset:32
	ds_read_b64_tr_b16 v[182:183], v165 offset:64
	ds_read_b64_tr_b16 v[186:187], v165 offset:96
	ds_read_b64_tr_b16 v[180:181], v165 offset:2592
	ds_read_b64_tr_b16 v[184:185], v165 offset:2624
	ds_read_b64_tr_b16 v[188:189], v165 offset:2656
	s_waitcnt lgkmcnt(6)
	v_mfma_f32_16x16x32_bf16 v[174:177], v[104:107], v[174:177], 0
	v_cvt_pk_bf16_f32 v166, v72, v73
	v_cvt_pk_bf16_f32 v167, v74, v75
	v_cvt_pk_bf16_f32 v168, v84, v85
	s_waitcnt lgkmcnt(2)
	v_mfma_f32_16x16x32_bf16 v[178:181], v[104:107], v[178:181], 0
	v_cvt_pk_bf16_f32 v169, v86, v87
	ds_read_b64_tr_b16 v[192:193], v165 offset:7680
	ds_read_b64_tr_b16 v[190:191], v165 offset:5120
	ds_read_b64_tr_b16 v[194:195], v165 offset:5152
	ds_read_b64_tr_b16 v[198:199], v165 offset:5184
	ds_read_b64_tr_b16 v[202:203], v165 offset:5216
	ds_read_b64_tr_b16 v[196:197], v165 offset:7712
	ds_read_b64_tr_b16 v[200:201], v165 offset:7744
	ds_read_b64_tr_b16 v[204:205], v165 offset:7776
	v_cvt_pk_bf16_f32 v170, v64, v65
	s_waitcnt lgkmcnt(6)
	v_mfma_f32_16x16x32_bf16 v[174:177], v[108:111], v[190:193], v[174:177]
	ds_read_b64_tr_b16 v[192:193], v165 offset:12800
	ds_read_b64_tr_b16 v[190:191], v165 offset:10240
	ds_read_b64_tr_b16 v[206:207], v165 offset:10272
	ds_read_b64_tr_b16 v[210:211], v165 offset:10304
	ds_read_b64_tr_b16 v[214:215], v165 offset:10336
	ds_read_b64_tr_b16 v[208:209], v165 offset:12832
	ds_read_b64_tr_b16 v[212:213], v165 offset:12864
	ds_read_b64_tr_b16 v[216:217], v165 offset:12896
	v_cvt_pk_bf16_f32 v171, v66, v67
	v_cvt_pk_bf16_f32 v172, v68, v69
	s_waitcnt lgkmcnt(10)
	v_mfma_f32_16x16x32_bf16 v[178:181], v[108:111], v[194:197], v[178:181]
	v_cvt_pk_bf16_f32 v173, v70, v71
	v_add_u32_e32 v234, v140, v142
	v_mov_b32_e32 v220, v115
	v_mfma_f32_16x16x32_bf16 v[182:185], v[104:107], v[182:185], 0
	v_mov_b32_e32 v221, v115
	s_and_b64 s[18:19], s[6:7], exec
	s_cselect_b32 s12, s22, s20
	s_waitcnt lgkmcnt(6)
	v_mfma_f32_16x16x32_bf16 v[174:177], v[166:169], v[190:193], v[174:177]
	ds_read_b64_tr_b16 v[192:193], v165 offset:17920
	ds_read_b64 v[218:219], v234 offset:40960
	ds_read_b64_tr_b16 v[190:191], v165 offset:15360
	ds_read_b64_tr_b16 v[222:223], v165 offset:15392
	ds_read_b64_tr_b16 v[226:227], v165 offset:15424
	ds_read_b64_tr_b16 v[230:231], v165 offset:15456
	ds_read_b64_tr_b16 v[224:225], v165 offset:17952
	ds_read_b64_tr_b16 v[228:229], v165 offset:17984
	ds_read_b64_tr_b16 v[232:233], v165 offset:18016
	v_add_u32_e32 v165, 0xa800, v234
	s_waitcnt lgkmcnt(11)
	v_mfma_f32_16x16x32_bf16 v[178:181], v[166:169], v[206:209], v[178:181]
	s_lshl_b64 s[18:19], s[12:13], 11
	v_mfma_f32_16x16x32_bf16 v[182:185], v[108:111], v[198:201], v[182:185]
	s_waitcnt lgkmcnt(6)
	v_mfma_f32_16x16x32_bf16 v[174:177], v[170:173], v[190:193], v[174:177]
	ds_read2_b64 v[192:195], v165 offset0:32 offset1:36
	v_add_u32_e32 v165, 0xb000, v234
	ds_read_b64 v[190:191], v234 offset:45632
	s_waitcnt lgkmcnt(4)
	v_mfma_f32_16x16x32_bf16 v[178:181], v[170:173], v[222:225], v[178:181]
	v_mfma_f32_16x16x32_bf16 v[182:185], v[166:169], v[210:213], v[182:185]
	v_mfma_f32_16x16x32_bf16 v[104:107], v[104:107], v[186:189], 0
	s_waitcnt lgkmcnt(1)
	v_mfma_f32_16x16x32_bf16 v[178:181], v[100:103], v[192:195], v[178:181]
	ds_read2_b64 v[192:195], v165 offset0:64 offset1:68
	v_add_u32_e32 v165, 0xb800, v234
	v_mfma_f32_16x16x32_bf16 v[182:185], v[170:173], v[226:229], v[182:185]
	v_mfma_f32_16x16x32_bf16 v[104:107], v[108:111], v[202:205], v[104:107]
	ds_read2_b64 v[108:111], v165 offset0:96 offset1:100
	s_waitcnt lgkmcnt(1)
	v_mfma_f32_16x16x32_bf16 v[182:185], v[100:103], v[192:195], v[182:185]
	v_mov_b32_e32 v192, v115
	v_mov_b32_e32 v193, v115
	v_mfma_f32_16x16x32_bf16 v[104:107], v[166:169], v[214:217], v[104:107]
	v_mfma_f32_16x16x32_bf16 v[174:177], v[100:103], v[218:221], v[174:177]
	v_mfma_f32_16x16x32_bf16 v[182:185], v[96:99], v[190:193], v[182:185]
	v_lshl_add_u64 v[190:191], v[118:119], 0, s[18:19]
	s_nop 5
	v_cvt_pk_bf16_f32 v174, v174, v175
	v_cvt_pk_bf16_f32 v175, v176, v177
	v_mfma_f32_16x16x32_bf16 v[104:107], v[170:173], v[230:233], v[104:107]
	v_lshl_add_u64 v[176:177], v[120:121], 1, v[190:191]
	global_store_dwordx2 v[176:177], v[174:175], off
	v_cvt_pk_bf16_f32 v174, v178, v179
	v_cvt_pk_bf16_f32 v175, v180, v181
	v_lshl_add_u64 v[166:167], v[122:123], 1, v[190:191]
	global_store_dwordx2 v[166:167], v[174:175], off
	ds_read2_b64 v[166:169], v165 offset0:104 offset1:108
	v_add_u32_e32 v165, v140, v144
	v_add_u32_e32 v174, v140, v116
	ds_read_b128 v[192:195], v174 offset:50176
	ds_read_b64 v[196:197], v165 offset:20480
	ds_read_b64 v[198:199], v165 offset:20512
	ds_read_b64 v[200:201], v165 offset:20544
	ds_read_b64 v[202:203], v165 offset:20576
	ds_read_b128 v[204:207], v174 offset:50240
	ds_read_b64 v[208:209], v165 offset:22656
	ds_read_b64 v[210:211], v165 offset:22688
	ds_read_b64 v[212:213], v165 offset:22720
	ds_read_b64 v[214:215], v165 offset:22752
	s_waitcnt lgkmcnt(11)
	v_mfma_f32_16x16x32_bf16 v[104:107], v[100:103], v[108:111], v[104:107]
	v_cvt_pk_bf16_f32 v170, v182, v183
	v_cvt_pk_bf16_f32 v171, v184, v185
	v_lshl_add_u64 v[108:109], v[124:125], 1, v[190:191]
	s_waitcnt lgkmcnt(10)
	v_mfma_f32_16x16x32_bf16 v[104:107], v[96:99], v[166:169], v[104:107]
	ds_read_b128 v[216:219], v174 offset:50304
	ds_read_b64 v[220:221], v165 offset:24832
	ds_read_b64 v[222:223], v165 offset:24864
	ds_read_b64 v[224:225], v165 offset:24896
	ds_read_b64 v[226:227], v165 offset:24928
	global_store_dwordx2 v[108:109], v[170:171], off
	s_nop 6
	v_cvt_pk_bf16_f32 v104, v104, v105
	v_cvt_pk_bf16_f32 v105, v106, v107
	v_lshl_add_u64 v[106:107], v[126:127], 1, v[190:191]
	global_store_dwordx2 v[106:107], v[104:105], off
	s_branch .Lsu1_main
; #define LAS __attribute__((address_space(3)))
; __device__ __forceinline__ void hgrn_scan(const Params& p, LAS unsigned char* lds, int chain) {
;     ...
; #pragma unroll
;         for (int blk = 0; blk < 8; ++blk) {
;             const f32x4 d4 = *(const LAS f32x4*)(bb + SB_D + (16 * blk + 4 * g) * 4);
;             f32x4 s = S[blk] * d4;
; #pragma unroll
;             for (int sp = 0; sp < 2; ++sp) {
;                 const LAS unsigned char* kp = bb + SB_KD + (16 * blk + li) * HPK + (32 * sp + 4 * g) * 2;
;                 s = __builtin_amdgcn_mfma_f32_16x16x32_bf16(cat8u(*(const LAS u32x2*)kp, *(const LAS u32x2*)(kp + 32)), vf[sp], s, 0, 0, 0);
;             }
;             S[blk] = s;
;         }
.LBB0_412:
	v_add_u32_e32 v165, v140, v144
	v_add_u32_e32 v174, v140, v116
	ds_read_b128 v[192:195], v174 offset:50176
	ds_read_b64 v[196:197], v165 offset:20480
	ds_read_b64 v[198:199], v165 offset:20512
	ds_read_b64 v[200:201], v165 offset:20544
	ds_read_b64 v[202:203], v165 offset:20576
	ds_read_b128 v[204:207], v174 offset:50240
	ds_read_b64 v[208:209], v165 offset:22656
	ds_read_b64 v[210:211], v165 offset:22688
	ds_read_b64 v[212:213], v165 offset:22720
	ds_read_b64 v[214:215], v165 offset:22752
	s_waitcnt lgkmcnt(10)
	ds_read_b128 v[216:219], v174 offset:50304
	ds_read_b64 v[220:221], v165 offset:24832
	ds_read_b64 v[222:223], v165 offset:24864
	ds_read_b64 v[224:225], v165 offset:24896
	ds_read_b64 v[226:227], v165 offset:24928
.Lsu1_main:
	s_waitcnt lgkmcnt(5)
	v_pk_mul_f32 v[76:77], v[76:77], v[192:193]
	v_pk_mul_f32 v[78:79], v[78:79], v[194:195]
	v_pk_mul_f32 v[92:93], v[92:93], v[204:205]
	v_pk_mul_f32 v[94:95], v[94:95], v[206:207]
	v_mfma_f32_16x16x32_bf16 v[76:79], v[196:199], v[100:103], v[76:79]
	s_nop 0
	v_mfma_f32_16x16x32_bf16 v[92:95], v[208:211], v[100:103], v[92:95]
	v_mfma_f32_16x16x32_bf16 v[76:79], v[200:203], v[96:99], v[76:79]
	v_mfma_f32_16x16x32_bf16 v[92:95], v[212:215], v[96:99], v[92:95]
	ds_read_b128 v[192:195], v174 offset:50368
	ds_read_b64 v[196:197], v165 offset:27008
	ds_read_b64 v[198:199], v165 offset:27040
	ds_read_b64 v[200:201], v165 offset:27072
	ds_read_b64 v[202:203], v165 offset:27104
	ds_read_b128 v[204:207], v174 offset:50432
	ds_read_b64 v[208:209], v165 offset:29184
	ds_read_b64 v[210:211], v165 offset:29216
	ds_read_b64 v[212:213], v165 offset:29248
	ds_read_b64 v[214:215], v165 offset:29280
	s_waitcnt lgkmcnt(5)
	v_pk_mul_f32 v[80:81], v[80:81], v[216:217]
	v_pk_mul_f32 v[82:83], v[82:83], v[218:219]
	v_pk_mul_f32 v[88:89], v[88:89], v[192:193]
	v_pk_mul_f32 v[90:91], v[90:91], v[194:195]
	v_mfma_f32_16x16x32_bf16 v[80:83], v[220:223], v[100:103], v[80:83]
	s_nop 0
	v_mfma_f32_16x16x32_bf16 v[88:91], v[196:199], v[100:103], v[88:91]
	v_mfma_f32_16x16x32_bf16 v[80:83], v[224:227], v[96:99], v[80:83]
	v_mfma_f32_16x16x32_bf16 v[88:91], v[200:203], v[96:99], v[88:91]
	ds_read_b128 v[216:219], v174 offset:50496
	ds_read_b64 v[220:221], v165 offset:31360
	ds_read_b64 v[222:223], v165 offset:31392
	ds_read_b64 v[224:225], v165 offset:31424
	ds_read_b64 v[226:227], v165 offset:31456
	ds_read_b128 v[192:195], v174 offset:50560
	ds_read_b64 v[196:197], v165 offset:33536
	ds_read_b64 v[198:199], v165 offset:33568
	ds_read_b64 v[200:201], v165 offset:33600
	ds_read_b64 v[202:203], v165 offset:33632
	s_waitcnt lgkmcnt(5)
	v_pk_mul_f32 v[72:73], v[72:73], v[204:205]
	v_pk_mul_f32 v[74:75], v[74:75], v[206:207]
	v_pk_mul_f32 v[84:85], v[84:85], v[216:217]
	v_pk_mul_f32 v[86:87], v[86:87], v[218:219]
	v_mfma_f32_16x16x32_bf16 v[72:75], v[208:211], v[100:103], v[72:75]
	s_nop 0
	v_mfma_f32_16x16x32_bf16 v[84:87], v[220:223], v[100:103], v[84:87]
	v_mfma_f32_16x16x32_bf16 v[72:75], v[212:215], v[96:99], v[72:75]
	v_mfma_f32_16x16x32_bf16 v[84:87], v[224:227], v[96:99], v[84:87]
	ds_read_b128 v[204:207], v174 offset:50624
	ds_read_b64 v[208:209], v165 offset:35712
	ds_read_b64 v[210:211], v165 offset:35744
	ds_read_b64 v[212:213], v165 offset:35776
	ds_read_b64 v[214:215], v165 offset:35808
	s_waitcnt lgkmcnt(0)
	v_pk_mul_f32 v[64:65], v[64:65], v[192:193]
	v_pk_mul_f32 v[66:67], v[66:67], v[194:195]
	v_pk_mul_f32 v[68:69], v[68:69], v[204:205]
	v_pk_mul_f32 v[70:71], v[70:71], v[206:207]
	v_mfma_f32_16x16x32_bf16 v[64:67], v[196:199], v[100:103], v[64:67]
	s_nop 0
	v_mfma_f32_16x16x32_bf16 v[68:71], v[208:211], v[100:103], v[68:71]
	v_mfma_f32_16x16x32_bf16 v[64:67], v[200:203], v[96:99], v[64:67]
	v_mfma_f32_16x16x32_bf16 v[68:71], v[212:215], v[96:99], v[68:71]
	s_cmp_lt_u32 s23, 3
	s_cbranch_scc1 .LBB0_414
	s_waitcnt vmcnt(6)
	ds_write_b128 v158, v[40:43]
	s_waitcnt vmcnt(5)
	ds_write_b128 v158, v[44:47] offset:10240
	s_waitcnt vmcnt(4)
	ds_write_b128 v159, v[56:59]

; #define LAS __attribute__((address_space(3)))
; __device__ __forceinline__ unsigned pk2(float lo, float hi) { const f32x2_t v = {lo, hi}; const bf16x2_t b = __builtin_convertvector(v, bf16x2_t); return __builtin_bit_cast(unsigned, b); }
; __device__ __forceinline__ bf16x8 cat8(const s16x4 a, const s16x4 b) { return __builtin_shufflevector(a, b, 0, 1, 2, 3, 4, 5, 6, 7); }
; __device__ __forceinline__ void hgrn_scan(const Params& p, LAS unsigned char* lds, int chain) {
;     ...
;         if (lat) {
;             bf16x8 sb[4];
; #pragma unroll
;             for (int ks = 0; ks < 4; ++ks) sb[ks] = pack_p(S[2 * ks], S[2 * ks + 1]);
;             bf16* orow = O + (long)hg_row(dir, b, 64 * c) * WA;
; #pragma unroll
;             for (int I = 0; I < 4; ++I) {
;                 f32x4 o = (f32x4){0.f, 0.f, 0.f, 0.f};
; #pragma unroll
;                 for (int ks = 0; ks < 4; ++ks) {
;                     const LAS unsigned char* ap = bb + SB_QD + (32 * ks + 4 * g + qq) * HP + (16 * I + 4 * pp) * 2;
;                     o = __builtin_amdgcn_mfma_f32_16x16x32_bf16(sb[ks], cat8(lds_tr(ap), lds_tr(ap + 16 * HP)), o, 0, 0, 0);
;                 }
; #pragma unroll
;                 for (int sp = 0; sp < 2; ++sp) {
;                     if (2 * sp > I) break;
;                     const LAS unsigned char* pr = bb + SB_P + (16 * I + li) * PP + (32 * sp + 4 * g) * 2;
;                     const u32x2 lo = *(const LAS u32x2*)pr; u32x2 hi = (u32x2){0u, 0u};
;                     if (2 * sp + 1 <= I) hi = *(const LAS u32x2*)(pr + 32);
;                     o = __builtin_amdgcn_mfma_f32_16x16x32_bf16(vf[sp], cat8u(lo, hi), o, 0, 0, 0);
;                 }
;                 { u32x2 w; w.x = pk2(o.x, o.y); w.y = pk2(o.z, o.w); *(u32x2*)(orow + (long)(16 * I + li) * ost) = w; }
;             }
;     ...
;         for (int blk = 0; blk < 8; ++blk) {
;             const f32x4 d4 = *(const LAS f32x4*)(bb + SB_D + (16 * blk + 4 * g) * 4);
;             f32x4 s = S[blk] * d4;
; #pragma unroll
;             for (int sp = 0; sp < 2; ++sp) {
;                 const LAS unsigned char* kp = bb + SB_KD + (16 * blk + li) * HPK + (32 * sp + 4 * g) * 2;
;                 s = __builtin_amdgcn_mfma_f32_16x16x32_bf16(cat8u(*(const LAS u32x2*)kp, *(const LAS u32x2*)(kp + 32)), vf[sp], s, 0, 0, 0);
.LBB0_424:
	s_andn2_b64 vcc, exec, s[16:17]
	s_cbranch_vccnz .LBB0_426
	v_cvt_pk_bf16_f32 v104, v76, v77
	v_cvt_pk_bf16_f32 v105, v78, v79
	v_cvt_pk_bf16_f32 v106, v92, v93
	v_cvt_pk_bf16_f32 v107, v94, v95
	ds_read_b64_tr_b16 v[176:177], v162 offset:2560
	ds_read_b64_tr_b16 v[174:175], v162
	ds_read_b64_tr_b16 v[178:179], v162 offset:32
	ds_read_b64_tr_b16 v[182:183], v162 offset:64
	ds_read_b64_tr_b16 v[186:187], v162 offset:96
	ds_read_b64_tr_b16 v[180:181], v162 offset:2592
	ds_read_b64_tr_b16 v[184:185], v162 offset:2624
	ds_read_b64_tr_b16 v[188:189], v162 offset:2656
	v_cvt_pk_bf16_f32 v108, v80, v81
	v_cvt_pk_bf16_f32 v109, v82, v83
	v_cvt_pk_bf16_f32 v110, v88, v89
	v_cvt_pk_bf16_f32 v111, v90, v91
	s_waitcnt lgkmcnt(6)
	v_mfma_f32_16x16x32_bf16 v[174:177], v[104:107], v[174:177], 0
	ds_read_b64_tr_b16 v[192:193], v162 offset:7680
	ds_read_b64_tr_b16 v[190:191], v162 offset:5120
	ds_read_b64_tr_b16 v[194:195], v162 offset:5152
	ds_read_b64_tr_b16 v[198:199], v162 offset:5184
	ds_read_b64_tr_b16 v[202:203], v162 offset:5216
	ds_read_b64_tr_b16 v[196:197], v162 offset:7712
	ds_read_b64_tr_b16 v[200:201], v162 offset:7744
	ds_read_b64_tr_b16 v[204:205], v162 offset:7776
	v_cvt_pk_bf16_f32 v166, v72, v73
	v_cvt_pk_bf16_f32 v167, v74, v75
	s_waitcnt lgkmcnt(10)
	v_mfma_f32_16x16x32_bf16 v[178:181], v[104:107], v[178:181], 0
	v_cvt_pk_bf16_f32 v168, v84, v85
	v_cvt_pk_bf16_f32 v169, v86, v87
	v_cvt_pk_bf16_f32 v170, v64, v65
	s_waitcnt lgkmcnt(6)
	v_mfma_f32_16x16x32_bf16 v[174:177], v[108:111], v[190:193], v[174:177]
	ds_read_b64_tr_b16 v[192:193], v162 offset:12800
	ds_read_b64_tr_b16 v[190:191], v162 offset:10240
	ds_read_b64_tr_b16 v[206:207], v162 offset:10272
	ds_read_b64_tr_b16 v[210:211], v162 offset:10304
	ds_read_b64_tr_b16 v[214:215], v162 offset:10336
	ds_read_b64_tr_b16 v[208:209], v162 offset:12832
	ds_read_b64_tr_b16 v[212:213], v162 offset:12864
	ds_read_b64_tr_b16 v[216:217], v162 offset:12896
	v_cvt_pk_bf16_f32 v171, v66, v67
	v_cvt_pk_bf16_f32 v172, v68, v69
	s_waitcnt lgkmcnt(10)
	v_mfma_f32_16x16x32_bf16 v[178:181], v[108:111], v[194:197], v[178:181]
	v_cvt_pk_bf16_f32 v173, v70, v71
	v_add_u32_e32 v165, 0x800, v163
	v_mov_b32_e32 v220, v115
	v_mfma_f32_16x16x32_bf16 v[182:185], v[104:107], v[182:185], 0
	v_mov_b32_e32 v221, v115
	s_add_i32 s12, s22, 64
	s_sub_i32 s18, s20, 64
	s_waitcnt lgkmcnt(6)
	v_mfma_f32_16x16x32_bf16 v[174:177], v[166:169], v[190:193], v[174:177]
	ds_read_b64_tr_b16 v[192:193], v162 offset:17920
	ds_read_b64 v[218:219], v163
	ds_read_b64_tr_b16 v[190:191], v162 offset:15360
	ds_read_b64_tr_b16 v[222:223], v162 offset:15392
	ds_read_b64_tr_b16 v[226:227], v162 offset:15424
	ds_read_b64_tr_b16 v[230:231], v162 offset:15456
	ds_read_b64_tr_b16 v[224:225], v162 offset:17952
	ds_read_b64_tr_b16 v[228:229], v162 offset:17984
	ds_read_b64_tr_b16 v[232:233], v162 offset:18016
	s_and_b64 s[16:17], s[6:7], exec
	s_cselect_b32 s12, s12, s18
	s_waitcnt lgkmcnt(11)
	v_mfma_f32_16x16x32_bf16 v[178:181], v[166:169], v[206:209], v[178:181]
	s_lshl_b64 s[16:17], s[12:13], 11
	v_mfma_f32_16x16x32_bf16 v[182:185], v[108:111], v[198:201], v[182:185]
	s_waitcnt lgkmcnt(6)
	v_mfma_f32_16x16x32_bf16 v[174:177], v[170:173], v[190:193], v[174:177]
	ds_read2_b64 v[192:195], v165 offset0:32 offset1:36
	v_add_u32_e32 v165, 0x1000, v163
	ds_read_b64 v[190:191], v163 offset:4672
	s_waitcnt lgkmcnt(4)
	v_mfma_f32_16x16x32_bf16 v[178:181], v[170:173], v[222:225], v[178:181]
	v_mfma_f32_16x16x32_bf16 v[182:185], v[166:169], v[210:213], v[182:185]
	v_mfma_f32_16x16x32_bf16 v[104:107], v[104:107], v[186:189], 0
	s_waitcnt lgkmcnt(1)
	v_mfma_f32_16x16x32_bf16 v[178:181], v[100:103], v[192:195], v[178:181]
	ds_read2_b64 v[192:195], v165 offset0:64 offset1:68
	v_add_u32_e32 v165, 0x1800, v163
	v_mfma_f32_16x16x32_bf16 v[182:185], v[170:173], v[226:229], v[182:185]
	v_mfma_f32_16x16x32_bf16 v[104:107], v[108:111], v[202:205], v[104:107]
	ds_read2_b64 v[108:111], v165 offset0:96 offset1:100
	s_waitcnt lgkmcnt(1)
	v_mfma_f32_16x16x32_bf16 v[182:185], v[100:103], v[192:195], v[182:185]
	v_mov_b32_e32 v192, v115
	v_mov_b32_e32 v193, v115
	v_mfma_f32_16x16x32_bf16 v[104:107], v[166:169], v[214:217], v[104:107]
	v_mfma_f32_16x16x32_bf16 v[174:177], v[100:103], v[218:221], v[174:177]
	v_mfma_f32_16x16x32_bf16 v[182:185], v[96:99], v[190:193], v[182:185]
	v_lshl_add_u64 v[190:191], v[118:119], 0, s[16:17]
	s_nop 5
	v_cvt_pk_bf16_f32 v174, v174, v175
	v_cvt_pk_bf16_f32 v175, v176, v177
	v_mfma_f32_16x16x32_bf16 v[104:107], v[170:173], v[230:233], v[104:107]
	v_lshl_add_u64 v[176:177], v[120:121], 1, v[190:191]
	global_store_dwordx2 v[176:177], v[174:175], off
	v_cvt_pk_bf16_f32 v174, v178, v179
	v_cvt_pk_bf16_f32 v175, v180, v181
	v_lshl_add_u64 v[166:167], v[122:123], 1, v[190:191]
	global_store_dwordx2 v[166:167], v[174:175], off
	ds_read2_b64 v[166:169], v165 offset0:104 offset1:108
	v_add_u32_e32 v165, v153, v144
	v_add_u32_e32 v174, 0x1d200, v143
	ds_read_b128 v[192:195], v174 offset:0
	ds_read_b64 v[196:197], v165 offset:0
	ds_read_b64 v[198:199], v165 offset:32
	ds_read_b64 v[200:201], v165 offset:64
	ds_read_b64 v[202:203], v165 offset:96
	ds_read_b128 v[204:207], v174 offset:64
	ds_read_b64 v[208:209], v165 offset:2176
	ds_read_b64 v[210:211], v165 offset:2208
	ds_read_b64 v[212:213], v165 offset:2240
	ds_read_b64 v[214:215], v165 offset:2272
	s_waitcnt lgkmcnt(11)
	v_mfma_f32_16x16x32_bf16 v[104:107], v[100:103], v[108:111], v[104:107]
	v_cvt_pk_bf16_f32 v170, v182, v183
	v_cvt_pk_bf16_f32 v171, v184, v185
	v_lshl_add_u64 v[108:109], v[124:125], 1, v[190:191]
	s_waitcnt lgkmcnt(10)
	v_mfma_f32_16x16x32_bf16 v[104:107], v[96:99], v[166:169], v[104:107]
	ds_read_b128 v[216:219], v174 offset:128
	ds_read_b64 v[220:221], v165 offset:4352
	ds_read_b64 v[222:223], v165 offset:4384
	ds_read_b64 v[224:225], v165 offset:4416
	ds_read_b64 v[226:227], v165 offset:4448
	global_store_dwordx2 v[108:109], v[170:171], off
	s_nop 6
	v_cvt_pk_bf16_f32 v104, v104, v105
	v_cvt_pk_bf16_f32 v105, v106, v107
	v_lshl_add_u64 v[106:107], v[126:127], 1, v[190:191]
	global_store_dwordx2 v[106:107], v[104:105], off
	s_branch .Lsu2_main
; #define LAS __attribute__((address_space(3)))
; __device__ __forceinline__ void hgrn_scan(const Params& p, LAS unsigned char* lds, int chain) {
;     ...
; #pragma unroll
;         for (int blk = 0; blk < 8; ++blk) {
;             const f32x4 d4 = *(const LAS f32x4*)(bb + SB_D + (16 * blk + 4 * g) * 4);
;             f32x4 s = S[blk] * d4;
; #pragma unroll
;             for (int sp = 0; sp < 2; ++sp) {
;                 const LAS unsigned char* kp = bb + SB_KD + (16 * blk + li) * HPK + (32 * sp + 4 * g) * 2;
;                 s = __builtin_amdgcn_mfma_f32_16x16x32_bf16(cat8u(*(const LAS u32x2*)kp, *(const LAS u32x2*)(kp + 32)), vf[sp], s, 0, 0, 0);
;             }
;             S[blk] = s;
;         }
.LBB0_426:
	v_add_u32_e32 v165, v153, v144
	v_add_u32_e32 v174, 0x1d200, v143
	ds_read_b128 v[192:195], v174 offset:0
	ds_read_b64 v[196:197], v165 offset:0
	ds_read_b64 v[198:199], v165 offset:32
	ds_read_b64 v[200:201], v165 offset:64
	ds_read_b64 v[202:203], v165 offset:96
	ds_read_b128 v[204:207], v174 offset:64
	ds_read_b64 v[208:209], v165 offset:2176
	ds_read_b64 v[210:211], v165 offset:2208
	ds_read_b64 v[212:213], v165 offset:2240
	ds_read_b64 v[214:215], v165 offset:2272
	s_waitcnt lgkmcnt(10)
	ds_read_b128 v[216:219], v174 offset:128
	ds_read_b64 v[220:221], v165 offset:4352
	ds_read_b64 v[222:223], v165 offset:4384
	ds_read_b64 v[224:225], v165 offset:4416
	ds_read_b64 v[226:227], v165 offset:4448
.Lsu2_main:
	s_waitcnt lgkmcnt(5)
	v_pk_mul_f32 v[76:77], v[76:77], v[192:193]
	v_pk_mul_f32 v[78:79], v[78:79], v[194:195]
	v_pk_mul_f32 v[92:93], v[92:93], v[204:205]
	v_pk_mul_f32 v[94:95], v[94:95], v[206:207]
	v_mfma_f32_16x16x32_bf16 v[76:79], v[196:199], v[100:103], v[76:79]
	s_nop 0
	v_mfma_f32_16x16x32_bf16 v[92:95], v[208:211], v[100:103], v[92:95]
	v_mfma_f32_16x16x32_bf16 v[76:79], v[200:203], v[96:99], v[76:79]
	v_mfma_f32_16x16x32_bf16 v[92:95], v[212:215], v[96:99], v[92:95]
	ds_read_b128 v[192:195], v174 offset:192
	ds_read_b64 v[196:197], v165 offset:6528
	ds_read_b64 v[198:199], v165 offset:6560
	ds_read_b64 v[200:201], v165 offset:6592
	ds_read_b64 v[202:203], v165 offset:6624
	ds_read_b128 v[204:207], v174 offset:256
	ds_read_b64 v[208:209], v165 offset:8704
	ds_read_b64 v[210:211], v165 offset:8736
	ds_read_b64 v[212:213], v165 offset:8768
	ds_read_b64 v[214:215], v165 offset:8800
	s_waitcnt lgkmcnt(5)
	v_pk_mul_f32 v[80:81], v[80:81], v[216:217]
	v_pk_mul_f32 v[82:83], v[82:83], v[218:219]
	v_pk_mul_f32 v[88:89], v[88:89], v[192:193]
	v_pk_mul_f32 v[90:91], v[90:91], v[194:195]
	v_mfma_f32_16x16x32_bf16 v[80:83], v[220:223], v[100:103], v[80:83]
	s_nop 0
	v_mfma_f32_16x16x32_bf16 v[88:91], v[196:199], v[100:103], v[88:91]
	v_mfma_f32_16x16x32_bf16 v[80:83], v[224:227], v[96:99], v[80:83]
	v_mfma_f32_16x16x32_bf16 v[88:91], v[200:203], v[96:99], v[88:91]
	ds_read_b128 v[216:219], v174 offset:320
	ds_read_b64 v[220:221], v165 offset:10880
	ds_read_b64 v[222:223], v165 offset:10912
	ds_read_b64 v[224:225], v165 offset:10944
	ds_read_b64 v[226:227], v165 offset:10976
	ds_read_b128 v[192:195], v174 offset:384
	ds_read_b64 v[196:197], v165 offset:13056
	ds_read_b64 v[198:199], v165 offset:13088
	ds_read_b64 v[200:201], v165 offset:13120
	ds_read_b64 v[202:203], v165 offset:13152
	s_waitcnt lgkmcnt(5)
	v_pk_mul_f32 v[72:73], v[72:73], v[204:205]
	v_pk_mul_f32 v[74:75], v[74:75], v[206:207]
	v_pk_mul_f32 v[84:85], v[84:85], v[216:217]
	v_pk_mul_f32 v[86:87], v[86:87], v[218:219]
	v_mfma_f32_16x16x32_bf16 v[72:75], v[208:211], v[100:103], v[72:75]
	s_nop 0
	v_mfma_f32_16x16x32_bf16 v[84:87], v[220:223], v[100:103], v[84:87]
	v_mfma_f32_16x16x32_bf16 v[72:75], v[212:215], v[96:99], v[72:75]
	v_mfma_f32_16x16x32_bf16 v[84:87], v[224:227], v[96:99], v[84:87]
	ds_read_b128 v[204:207], v174 offset:448
	ds_read_b64 v[208:209], v165 offset:15232
	ds_read_b64 v[210:211], v165 offset:15264
	ds_read_b64 v[212:213], v165 offset:15296
	ds_read_b64 v[214:215], v165 offset:15328
	s_waitcnt lgkmcnt(0)
	v_pk_mul_f32 v[64:65], v[64:65], v[192:193]
	v_pk_mul_f32 v[66:67], v[66:67], v[194:195]
	v_pk_mul_f32 v[68:69], v[68:69], v[204:205]
	v_pk_mul_f32 v[70:71], v[70:71], v[206:207]
	v_mfma_f32_16x16x32_bf16 v[64:67], v[196:199], v[100:103], v[64:67]
	s_nop 0
	v_mfma_f32_16x16x32_bf16 v[68:71], v[208:211], v[100:103], v[68:71]
	v_mfma_f32_16x16x32_bf16 v[64:67], v[200:203], v[96:99], v[64:67]
	v_mfma_f32_16x16x32_bf16 v[68:71], v[212:215], v[96:99], v[68:71]
	s_add_i32 s12, s30, 3
	s_cmp_gt_u32 s12, 34
	s_cbranch_scc1 .LBB0_432
	s_cmp_eq_u32 s14, 0
	s_cbranch_scc1 .LBB0_429
	v_add_u32_e32 v96, v154, v113
	ds_write_b128 v96, v[48:51]
	ds_write_b128 v96, v[52:55] offset:10240
	ds_write_b128 v164, v[60:63] offset:40960
